# v52 + attention unit epilogues: 8 dwordx2 row-per-lane stores paired into 4 dwordx4 via v_permlane32_swap (guide 7.3)
# speedup vs baseline: 1.0059x; 1.0059x over previous
.LBB0_394:
	v_readlane_b32 s4, v236, 60
	s_add_u32 s4, s4, s6
	v_readlane_b32 s6, v236, 57
	s_addc_u32 s6, s6, s7
	v_exp_f32_e32 v7, v81
	v_exp_f32_e32 v8, v80
	v_exp_f32_e32 v9, v83
	v_exp_f32_e32 v10, v82
	v_exp_f32_e32 v11, v85
	v_exp_f32_e32 v12, v84
	v_exp_f32_e32 v13, v87
	v_exp_f32_e32 v66, v86
	v_exp_f32_e32 v67, v89
	v_exp_f32_e32 v68, v88
	v_exp_f32_e32 v27, v27
	v_exp_f32_e32 v26, v26
	v_exp_f32_e32 v69, v91
	v_exp_f32_e32 v70, v90
	v_exp_f32_e32 v65, v65
	v_exp_f32_e32 v64, v64
	v_add_f32_e32 v2, v7, v8
	v_add_f32_e32 v2, v9, v2
	v_add_f32_e32 v2, v10, v2
	v_add_f32_e32 v2, v11, v2
	v_add_f32_e32 v2, v12, v2
	v_add_f32_e32 v2, v13, v2
	v_add_f32_e32 v2, v66, v2
	v_add_f32_e32 v2, v67, v2
	v_add_f32_e32 v2, v68, v2
	v_add_f32_e32 v2, v27, v2
	v_add_f32_e32 v2, v26, v2
	v_add_u32_e32 v0, s5, v0
	s_waitcnt vmcnt(0)
	s_barrier
	v_add_f32_e32 v77, v69, v2
	ds_read_b64_tr_b16 v[2:3], v0 offset:8192
	ds_read_b64_tr_b16 v[4:5], v0 offset:8704
	v_exp_f32_e32 v71, v15
	v_cvt_pk_bf16_f32 v8, v7, v8
	v_cvt_pk_bf16_f32 v9, v9, v10
	v_cvt_pk_bf16_f32 v10, v11, v12
	v_cvt_pk_bf16_f32 v11, v13, v66
	v_exp_f32_e32 v72, v14
	v_exp_f32_e32 v73, v17
	s_waitcnt lgkmcnt(0)
	v_mfma_f32_32x32x16_bf16 v[32:47], v[2:5], v[8:11], v[32:47]
	v_add_f32_e32 v2, v70, v77
	v_exp_f32_e32 v74, v16
	v_exp_f32_e32 v75, v19
	v_exp_f32_e32 v76, v18
	ds_read_b64_tr_b16 v[12:13], v0 offset:12288
	ds_read_b64_tr_b16 v[14:15], v0 offset:12800
	ds_read_b64_tr_b16 v[16:17], v0 offset:9216
	ds_read_b64_tr_b16 v[18:19], v0 offset:9728
	v_add_f32_e32 v2, v65, v2
	v_add_f32_e32 v2, v64, v2
	v_add_f32_e32 v2, v71, v2
	v_add_f32_e32 v7, v72, v2
	s_waitcnt lgkmcnt(2)
	v_mfma_f32_32x32x16_bf16 v[48:63], v[12:15], v[8:11], v[48:63]
	v_exp_f32_e32 v21, v21
	v_add_f32_e32 v7, v73, v7
	v_exp_f32_e32 v20, v20
	v_add_f32_e32 v7, v74, v7
	v_exp_f32_e32 v23, v23
	ds_read_b64_tr_b16 v[2:3], v0 offset:13312
	ds_read_b64_tr_b16 v[4:5], v0 offset:13824
	v_add_f32_e32 v7, v75, v7
	v_exp_f32_e32 v22, v22
	v_cvt_pk_bf16_f32 v8, v67, v68
	v_cvt_pk_bf16_f32 v9, v27, v26
	v_cvt_pk_bf16_f32 v10, v69, v70
	v_cvt_pk_bf16_f32 v11, v65, v64
	v_add_f32_e32 v7, v76, v7
	v_exp_f32_e32 v25, v25
	s_waitcnt lgkmcnt(2)
	v_mfma_f32_32x32x16_bf16 v[32:47], v[16:19], v[8:11], v[32:47]
	v_add_f32_e32 v7, v21, v7
	v_exp_f32_e32 v24, v24
	v_add_f32_e32 v7, v20, v7
	v_exp_f32_e32 v29, v29
	v_add_f32_e32 v7, v23, v7
	v_exp_f32_e32 v28, v28
	ds_read_b64_tr_b16 v[16:17], v0 offset:10240
	ds_read_b64_tr_b16 v[18:19], v0 offset:10752
	s_waitcnt lgkmcnt(2)
	v_mfma_f32_32x32x16_bf16 v[48:63], v[2:5], v[8:11], v[48:63]
	v_add_f32_e32 v7, v22, v7
	v_exp_f32_e32 v31, v31
	v_add_f32_e32 v7, v25, v7
	v_exp_f32_e32 v30, v30
	v_add_f32_e32 v7, v24, v7
	v_add_f32_e32 v7, v29, v7
	v_cvt_pk_bf16_f32 v12, v71, v72
	v_cvt_pk_bf16_f32 v13, v73, v74
	v_cvt_pk_bf16_f32 v14, v75, v76
	v_cvt_pk_bf16_f32 v15, v21, v20
	v_add_f32_e32 v7, v28, v7
	ds_read_b64_tr_b16 v[2:3], v0 offset:14336
	ds_read_b64_tr_b16 v[4:5], v0 offset:14848
	ds_read_b64_tr_b16 v[8:9], v0 offset:11264
	ds_read_b64_tr_b16 v[10:11], v0 offset:11776
	s_waitcnt lgkmcnt(4)
	v_mfma_f32_32x32x16_bf16 v[32:47], v[16:19], v[12:15], v[32:47]
	ds_read_b64_tr_b16 v[16:17], v0 offset:15360
	ds_read_b64_tr_b16 v[18:19], v0 offset:15872
	v_add_f32_e32 v0, v31, v7
	v_add_f32_e32 v0, v30, v0
	v_add_f32_e32 v0, v6, v0
	v_mov_b32_e32 v6, v0
	s_nop 1
	v_permlane32_swap_b32 v0, v6
	s_nop 1
	s_lshl_b64 s[2:3], s[2:3], 1
	s_waitcnt lgkmcnt(4)
	v_mfma_f32_32x32x16_bf16 v[48:63], v[2:5], v[12:15], v[48:63]
	v_add_f32_e32 v0, v0, v6
	v_div_scale_f32 v6, s[34:35], v0, v0, 1.0
	v_rcp_f32_e32 v7, v6
	v_cvt_pk_bf16_f32 v2, v23, v22
	v_cvt_pk_bf16_f32 v3, v25, v24
	v_cvt_pk_bf16_f32 v4, v29, v28
	v_cvt_pk_bf16_f32 v5, v31, v30
	s_add_u32 s2, s4, s2
	s_addc_u32 s3, s6, s3
	s_waitcnt lgkmcnt(2)
	v_mfma_f32_32x32x16_bf16 v[32:47], v[8:11], v[2:5], v[32:47]
	s_mov_b64 s[6:7], 0
	s_waitcnt lgkmcnt(0)
	v_mfma_f32_32x32x16_bf16 v[48:63], v[16:19], v[2:5], v[48:63]
	v_fma_f32 v2, -v6, v7, 1.0
	v_fmac_f32_e32 v7, v2, v7
	v_div_scale_f32 v2, vcc, 1.0, v0, 1.0
	v_mul_f32_e32 v3, v2, v7
	v_fma_f32 v4, -v6, v3, v2
	v_fmac_f32_e32 v3, v4, v7
	v_fma_f32 v2, -v6, v3, v2
	v_div_fmas_f32 v2, v2, v7, v3
	v_div_fixup_f32 v2, v2, v0, 1.0
	v_lshlrev_b64 v[4:5], 11, v[150:151]
	v_lshl_add_u64 v[4:5], s[2:3], 0, v[4:5]
	v_lshlrev_b32_e32 v0, 1, v158
	v_lshl_add_u64 v[4:5], v[4:5], 0, v[0:1]
	v_mbcnt_lo_u32_b32 v0, -1, 0
	v_mbcnt_hi_u32_b32 v0, -1, v0
	v_and_b32_e32 v0, 32, v0
	v_lshrrev_b32_e32 v0, 2, v0
	v_lshl_add_u64 v[4:5], v[4:5], 0, v[0:1]
	v_pk_mul_f32 v[32:33], v[32:33], v[2:3] op_sel_hi:[1,0]
	v_pk_mul_f32 v[34:35], v[34:35], v[2:3] op_sel_hi:[1,0]
	v_pk_mul_f32 v[36:37], v[36:37], v[2:3] op_sel_hi:[1,0]
	v_pk_mul_f32 v[38:39], v[38:39], v[2:3] op_sel_hi:[1,0]
	v_pk_mul_f32 v[40:41], v[40:41], v[2:3] op_sel_hi:[1,0]
	v_pk_mul_f32 v[42:43], v[42:43], v[2:3] op_sel_hi:[1,0]
	v_pk_mul_f32 v[44:45], v[44:45], v[2:3] op_sel_hi:[1,0]
	v_pk_mul_f32 v[46:47], v[46:47], v[2:3] op_sel_hi:[1,0]
	v_pk_mul_f32 v[48:49], v[48:49], v[2:3] op_sel_hi:[1,0]
	v_pk_mul_f32 v[50:51], v[50:51], v[2:3] op_sel_hi:[1,0]
	v_pk_mul_f32 v[52:53], v[52:53], v[2:3] op_sel_hi:[1,0]
	v_pk_mul_f32 v[54:55], v[54:55], v[2:3] op_sel_hi:[1,0]
	v_pk_mul_f32 v[56:57], v[56:57], v[2:3] op_sel_hi:[1,0]
	v_pk_mul_f32 v[58:59], v[58:59], v[2:3] op_sel_hi:[1,0]
	v_pk_mul_f32 v[60:61], v[60:61], v[2:3] op_sel_hi:[1,0]
	v_pk_mul_f32 v[62:63], v[62:63], v[2:3] op_sel_hi:[1,0]
	v_cvt_pk_bf16_f32 v32, v32, v33
	v_cvt_pk_bf16_f32 v33, v34, v35
	v_cvt_pk_bf16_f32 v34, v36, v37
	v_cvt_pk_bf16_f32 v35, v38, v39
	v_cvt_pk_bf16_f32 v36, v40, v41
	v_cvt_pk_bf16_f32 v37, v42, v43
	v_cvt_pk_bf16_f32 v38, v44, v45
	v_cvt_pk_bf16_f32 v39, v46, v47
	v_cvt_pk_bf16_f32 v48, v48, v49
	v_cvt_pk_bf16_f32 v49, v50, v51
	v_cvt_pk_bf16_f32 v50, v52, v53
	v_cvt_pk_bf16_f32 v51, v54, v55
	v_cvt_pk_bf16_f32 v52, v56, v57
	v_cvt_pk_bf16_f32 v53, v58, v59
	v_cvt_pk_bf16_f32 v54, v60, v61
	v_cvt_pk_bf16_f32 v55, v62, v63
	s_nop 1
	v_permlane32_swap_b32 v32, v34
	v_permlane32_swap_b32 v33, v35
	v_permlane32_swap_b32 v36, v38
	v_permlane32_swap_b32 v37, v39
	v_permlane32_swap_b32 v48, v50
	v_permlane32_swap_b32 v49, v51
	v_permlane32_swap_b32 v52, v54
	v_permlane32_swap_b32 v53, v55
	s_nop 1
	global_store_dwordx4 v[4:5], v[32:35], off
	global_store_dwordx4 v[4:5], v[36:39], off offset:32
	global_store_dwordx4 v[4:5], v[48:51], off offset:64
	global_store_dwordx4 v[4:5], v[52:55], off offset:96
	s_nop 1
	s_barrier
	s_mov_b64 s[2:3], -1

.LBB0_411:
	v_exp_f32_e32 v50, v50
	v_exp_f32_e32 v51, v51
	v_exp_f32_e32 v52, v52
	v_exp_f32_e32 v53, v53
	v_exp_f32_e32 v54, v54
	v_exp_f32_e32 v55, v55
	v_exp_f32_e32 v67, v38
	v_add_f32_e32 v38, v50, v51
	v_exp_f32_e32 v56, v56
	v_add_f32_e32 v38, v52, v38
	v_exp_f32_e32 v57, v57
	v_add_f32_e32 v38, v53, v38
	v_exp_f32_e32 v58, v58
	v_add_f32_e32 v38, v54, v38
	v_exp_f32_e32 v59, v59
	v_add_f32_e32 v38, v55, v38
	v_exp_f32_e32 v60, v60
	v_add_f32_e32 v38, v56, v38
	v_exp_f32_e32 v61, v61
	v_add_f32_e32 v38, v57, v38
	v_exp_f32_e32 v62, v62
	v_exp_f32_e32 v74, v46
	v_exp_f32_e32 v75, v47
	v_add_f32_e32 v38, v58, v38
	v_cvt_pk_bf16_f32 v46, v50, v51
	v_cvt_pk_bf16_f32 v47, v52, v53
	ds_read_b64_tr_b16 v[50:51], v0 offset:8192
	ds_read_b64_tr_b16 v[52:53], v0 offset:8704
	v_exp_f32_e32 v63, v63
	v_add_f32_e32 v38, v59, v38
	v_exp_f32_e32 v64, v64
	v_add_f32_e32 v38, v60, v38
	v_exp_f32_e32 v65, v65
	v_add_f32_e32 v38, v61, v38
	v_exp_f32_e32 v34, v34
	v_exp_f32_e32 v76, v48
	v_exp_f32_e32 v77, v49
	v_add_f32_e32 v38, v62, v38
	v_cvt_pk_bf16_f32 v48, v54, v55
	v_cvt_pk_bf16_f32 v49, v56, v57
	v_exp_f32_e32 v35, v35
	v_add_f32_e32 v38, v63, v38
	s_waitcnt lgkmcnt(0)
	v_mfma_f32_32x32x16_bf16 v[18:33], v[50:53], v[46:49], v[18:33]
	ds_read_b64_tr_b16 v[50:51], v0 offset:12288
	ds_read_b64_tr_b16 v[52:53], v0 offset:12800
	v_exp_f32_e32 v36, v36
	v_add_f32_e32 v38, v64, v38
	v_exp_f32_e32 v37, v37
	v_add_f32_e32 v38, v65, v38
	v_add_f32_e32 v38, v34, v38
	v_exp_f32_e32 v68, v39
	v_add_f32_e32 v38, v35, v38
	v_exp_f32_e32 v69, v40
	v_add_f32_e32 v38, v36, v38
	s_waitcnt lgkmcnt(0)
	v_mfma_f32_32x32x16_bf16 v[2:17], v[50:53], v[46:49], v[2:17]
	ds_read_b64_tr_b16 v[46:47], v0 offset:9216
	ds_read_b64_tr_b16 v[48:49], v0 offset:9728
	v_exp_f32_e32 v41, v41
	v_add_f32_e32 v38, v37, v38
	v_exp_f32_e32 v70, v42
	v_add_f32_e32 v38, v67, v38
	v_exp_f32_e32 v71, v43
	v_add_f32_e32 v38, v68, v38
	v_exp_f32_e32 v72, v44
	v_exp_f32_e32 v73, v45
	v_add_f32_e32 v38, v69, v38
	v_cvt_pk_bf16_f32 v42, v58, v59
	v_cvt_pk_bf16_f32 v43, v60, v61
	v_cvt_pk_bf16_f32 v44, v62, v63
	v_cvt_pk_bf16_f32 v45, v64, v65
	v_add_f32_e32 v38, v41, v38
	v_add_f32_e32 v38, v70, v38
	s_waitcnt lgkmcnt(0)
	v_mfma_f32_32x32x16_bf16 v[18:33], v[46:49], v[42:45], v[18:33]
	ds_read_b64_tr_b16 v[46:47], v0 offset:13312
	ds_read_b64_tr_b16 v[48:49], v0 offset:13824
	v_add_f32_e32 v38, v71, v38
	v_add_f32_e32 v38, v72, v38
	v_add_f32_e32 v38, v73, v38
	v_add_f32_e32 v38, v74, v38
	v_add_f32_e32 v38, v75, v38
	v_add_f32_e32 v38, v76, v38
	s_waitcnt lgkmcnt(0)
	v_mfma_f32_32x32x16_bf16 v[2:17], v[46:49], v[42:45], v[2:17]
	ds_read_b64_tr_b16 v[42:43], v0 offset:10240
	ds_read_b64_tr_b16 v[44:45], v0 offset:10752
	v_add_f32_e32 v38, v77, v38
	v_add_f32_e32 v66, v66, v38
	v_cvt_pk_bf16_f32 v38, v34, v35
	v_cvt_pk_bf16_f32 v39, v36, v37
	v_cvt_pk_bf16_f32 v40, v67, v68
	v_cvt_pk_bf16_f32 v41, v69, v41
	v_cvt_pk_bf16_f32 v34, v70, v71
	v_cvt_pk_bf16_f32 v35, v72, v73
	s_waitcnt lgkmcnt(0)
	v_mfma_f32_32x32x16_bf16 v[18:33], v[42:45], v[38:41], v[18:33]
	ds_read_b64_tr_b16 v[42:43], v0 offset:14336
	ds_read_b64_tr_b16 v[44:45], v0 offset:14848
	v_cvt_pk_bf16_f32 v36, v74, v75
	v_cvt_pk_bf16_f32 v37, v76, v77
	v_readlane_b32 s5, v235, 36
	s_add_u32 s4, s5, s4
	v_readlane_b32 s5, v235, 37
	s_addc_u32 s5, s5, 0
	s_waitcnt lgkmcnt(0)
	v_mfma_f32_32x32x16_bf16 v[2:17], v[42:45], v[38:41], v[2:17]
	ds_read_b64_tr_b16 v[38:39], v0 offset:11264
	ds_read_b64_tr_b16 v[40:41], v0 offset:11776
	s_lshl_b64 s[6:7], s[6:7], 1
	s_add_u32 s4, s4, s6
	s_addc_u32 s5, s5, s7
	s_waitcnt lgkmcnt(0)
	v_mfma_f32_32x32x16_bf16 v[18:33], v[38:41], v[34:37], v[18:33]
	ds_read_b64_tr_b16 v[38:39], v0 offset:15360
	ds_read_b64_tr_b16 v[40:41], v0 offset:15872
	v_mov_b32_e32 v0, v66
	s_nop 1
	v_permlane32_swap_b32 v66, v0
	s_nop 1
	s_nop 0
	v_add_f32_e32 v0, v66, v0
	s_waitcnt lgkmcnt(0)
	v_mfma_f32_32x32x16_bf16 v[2:17], v[38:41], v[34:37], v[2:17]
	v_div_scale_f32 v34, s[34:35], v0, v0, 1.0
	v_rcp_f32_e32 v35, v34
	s_nop 0
	v_fma_f32 v36, -v34, v35, 1.0
	v_fmac_f32_e32 v35, v36, v35
	v_div_scale_f32 v36, vcc, 1.0, v0, 1.0
	v_mul_f32_e32 v37, v36, v35
	v_fma_f32 v38, -v34, v37, v36
	v_fmac_f32_e32 v37, v38, v35
	v_fma_f32 v34, -v34, v37, v36
	v_div_fmas_f32 v34, v34, v35, v37
	v_div_fixup_f32 v34, v34, v0, 1.0
	v_lshlrev_b64 v[36:37], 11, v[114:115]
	v_lshl_add_u64 v[36:37], s[4:5], 0, v[36:37]
	v_lshlrev_b32_e32 v0, 1, v124
	s_andn2_b64 vcc, exec, s[48:49]
	v_lshl_add_u64 v[36:37], v[36:37], 0, v[0:1]
	v_mbcnt_lo_u32_b32 v0, -1, 0
	v_mbcnt_hi_u32_b32 v0, -1, v0
	v_and_b32_e32 v0, 32, v0
	v_lshrrev_b32_e32 v0, 2, v0
	v_lshl_add_u64 v[36:37], v[36:37], 0, v[0:1]
	v_pk_mul_f32 v[18:19], v[18:19], v[34:35] op_sel_hi:[1,0]
	v_pk_mul_f32 v[20:21], v[20:21], v[34:35] op_sel_hi:[1,0]
	v_pk_mul_f32 v[22:23], v[22:23], v[34:35] op_sel_hi:[1,0]
	v_pk_mul_f32 v[24:25], v[24:25], v[34:35] op_sel_hi:[1,0]
	v_pk_mul_f32 v[26:27], v[26:27], v[34:35] op_sel_hi:[1,0]
	v_pk_mul_f32 v[28:29], v[28:29], v[34:35] op_sel_hi:[1,0]
	v_pk_mul_f32 v[30:31], v[30:31], v[34:35] op_sel_hi:[1,0]
	v_pk_mul_f32 v[32:33], v[32:33], v[34:35] op_sel_hi:[1,0]
	v_pk_mul_f32 v[2:3], v[2:3], v[34:35] op_sel_hi:[1,0]
	v_pk_mul_f32 v[4:5], v[4:5], v[34:35] op_sel_hi:[1,0]
	v_pk_mul_f32 v[6:7], v[6:7], v[34:35] op_sel_hi:[1,0]
	v_pk_mul_f32 v[8:9], v[8:9], v[34:35] op_sel_hi:[1,0]
	v_pk_mul_f32 v[10:11], v[10:11], v[34:35] op_sel_hi:[1,0]
	v_pk_mul_f32 v[12:13], v[12:13], v[34:35] op_sel_hi:[1,0]
	v_pk_mul_f32 v[14:15], v[14:15], v[34:35] op_sel_hi:[1,0]
	v_pk_mul_f32 v[16:17], v[16:17], v[34:35] op_sel_hi:[1,0]
	v_cvt_pk_bf16_f32 v18, v18, v19
	v_cvt_pk_bf16_f32 v19, v20, v21
	v_cvt_pk_bf16_f32 v20, v22, v23
	v_cvt_pk_bf16_f32 v21, v24, v25
	v_cvt_pk_bf16_f32 v22, v26, v27
	v_cvt_pk_bf16_f32 v23, v28, v29
	v_cvt_pk_bf16_f32 v24, v30, v31
	v_cvt_pk_bf16_f32 v25, v32, v33
	v_cvt_pk_bf16_f32 v2, v2, v3
	v_cvt_pk_bf16_f32 v3, v4, v5
	v_cvt_pk_bf16_f32 v4, v6, v7
	v_cvt_pk_bf16_f32 v5, v8, v9
	v_cvt_pk_bf16_f32 v6, v10, v11
	v_cvt_pk_bf16_f32 v7, v12, v13
	v_cvt_pk_bf16_f32 v8, v14, v15
	v_cvt_pk_bf16_f32 v9, v16, v17
	s_nop 1
	v_permlane32_swap_b32 v18, v20
	v_permlane32_swap_b32 v19, v21
	v_permlane32_swap_b32 v22, v24
	v_permlane32_swap_b32 v23, v25
	v_permlane32_swap_b32 v2, v4
	v_permlane32_swap_b32 v3, v5
	v_permlane32_swap_b32 v6, v8
	v_permlane32_swap_b32 v7, v9
	s_nop 1
	global_store_dwordx4 v[36:37], v[18:21], off
	global_store_dwordx4 v[36:37], v[22:25], off offset:32
	global_store_dwordx4 v[36:37], v[2:5], off offset:64
	global_store_dwordx4 v[36:37], v[6:9], off offset:96
	s_nop 1
	s_cbranch_vccnz .LBB0_413
	s_barrier
	s_mov_b64 s[2:3], -1

.LBB0_442:
	v_exp_f32_e32 v66, v50
	v_exp_f32_e32 v67, v51
	v_exp_f32_e32 v69, v52
	v_exp_f32_e32 v70, v53
	v_exp_f32_e32 v71, v54
	v_exp_f32_e32 v72, v55
	v_exp_f32_e32 v50, v58
	v_exp_f32_e32 v58, v34
	v_add_f32_e32 v34, v66, v67
	v_exp_f32_e32 v73, v56
	v_add_f32_e32 v34, v69, v34
	v_exp_f32_e32 v74, v57
	v_add_f32_e32 v34, v70, v34
	v_add_f32_e32 v34, v71, v34
	v_exp_f32_e32 v51, v59
	v_add_f32_e32 v34, v72, v34
	v_exp_f32_e32 v52, v60
	v_add_f32_e32 v34, v73, v34
	v_exp_f32_e32 v53, v61
	v_add_f32_e32 v34, v74, v34
	v_exp_f32_e32 v54, v62
	v_add_f32_e32 v34, v50, v34
	v_add_f32_e32 v34, v51, v34
	v_add_f32_e32 v34, v52, v34
	v_add_f32_e32 v34, v53, v34
	v_exp_f32_e32 v59, v35
	v_exp_f32_e32 v60, v36
	v_exp_f32_e32 v61, v37
	v_add_f32_e32 v83, v54, v34
	ds_read_b64_tr_b16 v[34:35], v0 offset:12288
	ds_read_b64_tr_b16 v[36:37], v0 offset:12800
	v_exp_f32_e32 v55, v63
	v_exp_f32_e32 v56, v64
	v_exp_f32_e32 v57, v65
	v_exp_f32_e32 v62, v38
	v_exp_f32_e32 v63, v39
	v_exp_f32_e32 v64, v40
	v_exp_f32_e32 v65, v41
	v_cvt_pk_bf16_f32 v38, v66, v67
	v_cvt_pk_bf16_f32 v39, v69, v70
	v_cvt_pk_bf16_f32 v40, v71, v72
	v_cvt_pk_bf16_f32 v41, v73, v74
	v_exp_f32_e32 v75, v42
	v_exp_f32_e32 v76, v43
	s_waitcnt lgkmcnt(0)
	v_mfma_f32_32x32x16_bf16 v[18:33], v[34:37], v[38:41], v[18:33]
	v_add_f32_e32 v34, v55, v83
	v_add_f32_e32 v34, v56, v34
	v_exp_f32_e32 v77, v44
	v_exp_f32_e32 v78, v45
	v_exp_f32_e32 v79, v46
	v_exp_f32_e32 v80, v47
	v_exp_f32_e32 v81, v48
	v_exp_f32_e32 v82, v49
	ds_read_b64_tr_b16 v[42:43], v0 offset:16384
	ds_read_b64_tr_b16 v[44:45], v0 offset:16896
	ds_read_b64_tr_b16 v[46:47], v0 offset:13312
	ds_read_b64_tr_b16 v[48:49], v0 offset:13824
	v_add_f32_e32 v34, v57, v34
	v_add_f32_e32 v34, v58, v34
	v_add_f32_e32 v66, v59, v34
	s_waitcnt lgkmcnt(2)
	v_mfma_f32_32x32x16_bf16 v[2:17], v[42:45], v[38:41], v[2:17]
	v_add_f32_e32 v38, v60, v66
	v_add_f32_e32 v38, v61, v38
	v_add_f32_e32 v42, v62, v38
	v_cvt_pk_bf16_f32 v38, v50, v51
	v_cvt_pk_bf16_f32 v39, v52, v53
	v_cvt_pk_bf16_f32 v40, v54, v55
	v_cvt_pk_bf16_f32 v41, v56, v57
	ds_read_b64_tr_b16 v[34:35], v0 offset:17408
	ds_read_b64_tr_b16 v[36:37], v0 offset:17920
	s_waitcnt lgkmcnt(2)
	v_mfma_f32_32x32x16_bf16 v[18:33], v[46:49], v[38:41], v[18:33]
	ds_read_b64_tr_b16 v[46:47], v0 offset:14336
	ds_read_b64_tr_b16 v[48:49], v0 offset:14848
	v_add_f32_e32 v42, v63, v42
	v_add_f32_e32 v42, v64, v42
	v_add_f32_e32 v42, v65, v42
	v_add_f32_e32 v50, v75, v42
	v_cvt_pk_bf16_f32 v42, v58, v59
	v_cvt_pk_bf16_f32 v43, v60, v61
	s_waitcnt lgkmcnt(2)
	v_mfma_f32_32x32x16_bf16 v[2:17], v[34:37], v[38:41], v[2:17]
	v_cvt_pk_bf16_f32 v44, v62, v63
	v_cvt_pk_bf16_f32 v45, v64, v65
	ds_read_b64_tr_b16 v[34:35], v0 offset:18432
	ds_read_b64_tr_b16 v[36:37], v0 offset:18944
	ds_read_b64_tr_b16 v[38:39], v0 offset:15360
	ds_read_b64_tr_b16 v[40:41], v0 offset:15872
	s_lshl_b32 s27, s4, 7
	s_waitcnt lgkmcnt(4)
	v_mfma_f32_32x32x16_bf16 v[18:33], v[46:49], v[42:45], v[18:33]
	v_add_f32_e32 v46, v76, v50
	v_add_f32_e32 v46, v77, v46
	v_add_f32_e32 v46, v78, v46
	v_add_f32_e32 v46, v79, v46
	v_add_f32_e32 v50, v80, v46
	ds_read_b64_tr_b16 v[46:47], v0 offset:19456
	ds_read_b64_tr_b16 v[48:49], v0 offset:19968
	v_add_f32_e32 v0, v81, v50
	v_add_f32_e32 v0, v82, v0
	s_waitcnt lgkmcnt(4)
	v_mfma_f32_32x32x16_bf16 v[2:17], v[34:37], v[42:45], v[2:17]
	v_add_f32_e32 v0, v68, v0
	v_cvt_pk_bf16_f32 v34, v75, v76
	v_cvt_pk_bf16_f32 v35, v77, v78
	v_cvt_pk_bf16_f32 v36, v79, v80
	v_cvt_pk_bf16_f32 v37, v81, v82
	s_waitcnt lgkmcnt(2)
	s_nop 0
	v_mfma_f32_32x32x16_bf16 v[18:33], v[38:41], v[34:37], v[18:33]
	v_mov_b32_e32 v38, v0
	s_nop 1
	v_permlane32_swap_b32 v0, v38
	s_nop 1
	s_nop 0
	v_add_f32_e32 v0, v0, v38
	v_div_scale_f32 v38, s[4:5], v0, v0, 1.0
	v_rcp_f32_e32 v39, v38
	s_waitcnt lgkmcnt(0)
	v_mfma_f32_32x32x16_bf16 v[2:17], v[46:49], v[34:37], v[2:17]
	v_readlane_b32 s4, v235, 40
	s_add_u32 s27, s4, s27
	v_fma_f32 v34, -v38, v39, 1.0
	v_fmac_f32_e32 v39, v34, v39
	v_div_scale_f32 v34, vcc, 1.0, v0, 1.0
	v_mul_f32_e32 v35, v34, v39
	v_fma_f32 v36, -v38, v35, v34
	v_readlane_b32 s4, v235, 41
	v_fmac_f32_e32 v35, v36, v39
	s_addc_u32 s28, s4, 0
	v_fma_f32 v34, -v38, v35, v34
	s_lshl_b64 s[4:5], s[6:7], 1
	v_div_fmas_f32 v34, v34, v39, v35
	s_add_u32 s4, s27, s4
	v_div_fixup_f32 v34, v34, v0, 1.0
	s_addc_u32 s5, s28, s5
	v_lshlrev_b64 v[36:37], 11, v[122:123]
	v_lshl_add_u64 v[36:37], s[4:5], 0, v[36:37]
	v_lshlrev_b32_e32 v0, 1, v132
	s_andn2_b64 vcc, exec, s[48:49]
	v_lshl_add_u64 v[36:37], v[36:37], 0, v[0:1]
	v_mbcnt_lo_u32_b32 v0, -1, 0
	v_mbcnt_hi_u32_b32 v0, -1, v0
	v_and_b32_e32 v0, 32, v0
	v_lshrrev_b32_e32 v0, 2, v0
	v_lshl_add_u64 v[36:37], v[36:37], 0, v[0:1]
	v_pk_mul_f32 v[18:19], v[18:19], v[34:35] op_sel_hi:[1,0]
	v_pk_mul_f32 v[20:21], v[20:21], v[34:35] op_sel_hi:[1,0]
	v_pk_mul_f32 v[22:23], v[22:23], v[34:35] op_sel_hi:[1,0]
	v_pk_mul_f32 v[24:25], v[24:25], v[34:35] op_sel_hi:[1,0]
	v_pk_mul_f32 v[26:27], v[26:27], v[34:35] op_sel_hi:[1,0]
	v_pk_mul_f32 v[28:29], v[28:29], v[34:35] op_sel_hi:[1,0]
	v_pk_mul_f32 v[30:31], v[30:31], v[34:35] op_sel_hi:[1,0]
	v_pk_mul_f32 v[32:33], v[32:33], v[34:35] op_sel_hi:[1,0]
	v_pk_mul_f32 v[2:3], v[2:3], v[34:35] op_sel_hi:[1,0]
	v_pk_mul_f32 v[4:5], v[4:5], v[34:35] op_sel_hi:[1,0]
	v_pk_mul_f32 v[6:7], v[6:7], v[34:35] op_sel_hi:[1,0]
	v_pk_mul_f32 v[8:9], v[8:9], v[34:35] op_sel_hi:[1,0]
	v_pk_mul_f32 v[10:11], v[10:11], v[34:35] op_sel_hi:[1,0]
	v_pk_mul_f32 v[12:13], v[12:13], v[34:35] op_sel_hi:[1,0]
	v_pk_mul_f32 v[14:15], v[14:15], v[34:35] op_sel_hi:[1,0]
	v_pk_mul_f32 v[16:17], v[16:17], v[34:35] op_sel_hi:[1,0]
	v_cvt_pk_bf16_f32 v18, v18, v19
	v_cvt_pk_bf16_f32 v19, v20, v21
	v_cvt_pk_bf16_f32 v20, v22, v23
	v_cvt_pk_bf16_f32 v21, v24, v25
	v_cvt_pk_bf16_f32 v22, v26, v27
	v_cvt_pk_bf16_f32 v23, v28, v29
	v_cvt_pk_bf16_f32 v24, v30, v31
	v_cvt_pk_bf16_f32 v25, v32, v33
	v_cvt_pk_bf16_f32 v2, v2, v3
	v_cvt_pk_bf16_f32 v3, v4, v5
	v_cvt_pk_bf16_f32 v4, v6, v7
	v_cvt_pk_bf16_f32 v5, v8, v9
	v_cvt_pk_bf16_f32 v6, v10, v11
	v_cvt_pk_bf16_f32 v7, v12, v13
	v_cvt_pk_bf16_f32 v8, v14, v15
	v_cvt_pk_bf16_f32 v9, v16, v17
	s_nop 1
	v_permlane32_swap_b32 v18, v20
	v_permlane32_swap_b32 v19, v21
	v_permlane32_swap_b32 v22, v24
	v_permlane32_swap_b32 v23, v25
	v_permlane32_swap_b32 v2, v4
	v_permlane32_swap_b32 v3, v5
	v_permlane32_swap_b32 v6, v8
	v_permlane32_swap_b32 v7, v9
	s_nop 1
	global_store_dwordx4 v[36:37], v[18:21], off
	global_store_dwordx4 v[36:37], v[22:25], off offset:32
	global_store_dwordx4 v[36:37], v[2:5], off offset:64
	global_store_dwordx4 v[36:37], v[6:9], off offset:96
	s_nop 1
	s_cbranch_vccnz .LBB0_444
	s_mov_b64 s[2:3], -1
	s_barrier
